# baseline (speedup 1.0000x reference)
.LBB0_826:
	s_or_b64 exec, exec, s[24:25]
	s_waitcnt vmcnt(0)
	v_add_u32_e32 v0, 1, v222
	s_waitcnt vmcnt(0) lgkmcnt(0)
	s_barrier
	s_mov_b64 s[4:5], exec
	v_readlane_b32 s6, v255, 3
	v_readlane_b32 s7, v255, 4
	s_and_b64 s[6:7], s[4:5], s[6:7]
	s_xor_b64 s[4:5], s[6:7], s[4:5]
	s_mov_b64 exec, s[6:7]
	v_add_u32_e32 v0, 1, v222
	s_andn2_saveexec_b64 s[4:5], s[4:5]
	s_cbranch_execz .LBB0_102
	s_mov_b64 s[6:7], exec
	v_mbcnt_lo_u32_b32 v2, s6, 0
	v_mbcnt_hi_u32_b32 v2, s7, v2
	v_cmp_eq_u32_e32 vcc, 0, v2
	s_waitcnt vmcnt(0) expcnt(0) lgkmcnt(0)
	s_and_saveexec_b64 s[24:25], vcc
	s_cbranch_execz .LBB0_831
	s_bcnt1_i32_b64 s2, s[6:7]
	v_readlane_b32 s6, v255, 23
	v_mov_b32_e32 v3, s2
	v_readlane_b32 s7, v255, 24
	buffer_wbl2 sc1
	s_waitcnt vmcnt(0)
	global_atomic_add v3, v1, v3, s[6:7] sc0
